# P5 gate loads marked nt (streamed once per pass) so they do not displace the GEMM operand tiles in L2
# baseline (speedup 1.0000x reference)
;     __device__ __forceinline__ void rescale(f32x4 (&acc)[2][2][4][2], const Unit& u, int seg, int wr, int wc, int fr, int fq) const {
;         int t2_ = threadIdx.x; asm volatile("" : "+v"(t2_)); (void)wr; (void)wc; (void)fr; (void)fq;
;         const int row0 = u.pm * BM + ((t2_ >> 8) & 1) * 64 + (t2_ & 15), col0 = u.pn * BM + ((t2_ >> 6) & 3) * 32 + 8 * ((t2_ >> 4) & 3);
; #pragma unroll
;         for (int ai = 0; ai < 2; ++ai)
; #pragma unroll
;             for (int m = 0; m < 4; ++m) {
;                 const bf16_t* gp = Gt + (size_t)(row0 + ai * HALF + m * 16) * NP + seg * 2048 + col0;
; #pragma unroll
;                 for (int bj = 0; bj < 2; ++bj) {
;                     const u32x4 ga = *(const u32x4*)(gp + bj * HALF), gb = *(const u32x4*)(gp + bj * HALF + 2048);
;                     float fa[8], fb[8]; unpack8(ga, fa); unpack8(gb, fb);
; #pragma unroll
;                     for (int j = 0; j < 4; ++j) { acc[ai][bj][m][0][j] *= __fdividef(fa[j], fb[j]); acc[ai][bj][m][1][j] *= __fdividef(fa[4 + j], fb[4 + j]); }
;                     asm volatile("" : "+v"(acc[ai][bj][m][0]), "+v"(acc[ai][bj][m][1]) :: "memory");
;                 }
;             }
.LBB0_880:
	v_mov_b32_e32 v2, v210
	v_lshrrev_b32_e32 v1, 2, v2
	v_and_b32_e32 v3, 15, v2
	v_lshrrev_b32_e32 v2, 1, v2
	v_and_b32_e32 v1, 64, v1
	v_and_b32_e32 v2, 0x78, v2
	v_or3_b32 v1, v3, v1, s9
	v_or_b32_e32 v2, s51, v2
	s_cmpk_eq_i32 s36, 0x400
	s_cselect_b32 s94, 0, 0x1000
	v_mul_u32_u24_e32 v1, 0x5c00, v1
	v_lshl_add_u32 v1, v2, 1, v1
	s_add_u32 s100, s46, 0x1000
	s_addc_u32 s101, s47, 0
	v_add_u32_e32 v1, s94, v1
	v_add_u32_e32 v2, 0x5c000, v1
	v_add_u32_e32 v3, 0xb8000, v1
	v_add_u32_e32 v177, 0x114000, v1
	global_load_dwordx4 v[132:135], v1, s[46:47] offset:0 nt
	global_load_dwordx4 v[136:139], v1, s[100:101] offset:0 nt
	global_load_dwordx4 v[156:159], v1, s[46:47] offset:256 nt
	global_load_dwordx4 v[186:189], v1, s[100:101] offset:256 nt
	global_load_dwordx4 v[190:193], v2, s[46:47] offset:0 nt
	global_load_dwordx4 v[194:197], v2, s[100:101] offset:0 nt
	global_load_dwordx4 v[198:201], v2, s[46:47] offset:256 nt
	global_load_dwordx4 v[202:205], v2, s[100:101] offset:256 nt
	global_load_dwordx4 v[206:209], v3, s[46:47] offset:0 nt
	global_load_dwordx4 v[222:225], v3, s[100:101] offset:0 nt
	global_load_dwordx4 v[226:229], v3, s[46:47] offset:256 nt
	global_load_dwordx4 v[230:233], v3, s[100:101] offset:256 nt
	global_load_dwordx4 v[234:237], v177, s[46:47] offset:0 nt
	global_load_dwordx4 v[238:241], v177, s[100:101] offset:0 nt
	global_load_dwordx4 v[242:245], v177, s[46:47] offset:256 nt
	global_load_dwordx4 v[246:249], v177, s[100:101] offset:256 nt
	s_waitcnt vmcnt(14)
	v_lshlrev_b32_e32 v160, 16, v136
	v_and_b32_e32 v161, 0xffff0000, v136
	v_rcp_f32_e32 v160, v160
	v_rcp_f32_e32 v161, v161
	v_lshlrev_b32_e32 v2, 16, v132
	v_and_b32_e32 v3, 0xffff0000, v132
	v_pk_mul_f32 v[2:3], v[2:3], v[160:161]
	v_pk_mul_f32 v[128:129], v[128:129], v[2:3]
	v_lshlrev_b32_e32 v160, 16, v137
	v_and_b32_e32 v161, 0xffff0000, v137
	v_rcp_f32_e32 v160, v160
	v_rcp_f32_e32 v161, v161
	v_lshlrev_b32_e32 v2, 16, v133
	v_and_b32_e32 v3, 0xffff0000, v133
	v_pk_mul_f32 v[2:3], v[2:3], v[160:161]
	v_pk_mul_f32 v[130:131], v[130:131], v[2:3]
	v_lshlrev_b32_e32 v160, 16, v138
	v_and_b32_e32 v161, 0xffff0000, v138
	v_rcp_f32_e32 v160, v160
	v_rcp_f32_e32 v161, v161
	v_lshlrev_b32_e32 v2, 16, v134
	v_and_b32_e32 v3, 0xffff0000, v134
	v_pk_mul_f32 v[2:3], v[2:3], v[160:161]
	v_pk_mul_f32 v[124:125], v[124:125], v[2:3]
	v_lshlrev_b32_e32 v160, 16, v139
	v_and_b32_e32 v161, 0xffff0000, v139
	v_rcp_f32_e32 v160, v160
	v_rcp_f32_e32 v161, v161
	v_lshlrev_b32_e32 v2, 16, v135
	v_and_b32_e32 v3, 0xffff0000, v135
	v_pk_mul_f32 v[2:3], v[2:3], v[160:161]
	v_pk_mul_f32 v[126:127], v[126:127], v[2:3]
	v_add_u32_e32 v175, 0x2e0000, v1
	global_load_dwordx4 v[132:135], v175, s[46:47] offset:0 nt
	global_load_dwordx4 v[136:139], v175, s[100:101] offset:0 nt
	s_waitcnt vmcnt(14)
	v_lshlrev_b32_e32 v160, 16, v186
	v_and_b32_e32 v161, 0xffff0000, v186
	v_rcp_f32_e32 v160, v160
	v_rcp_f32_e32 v161, v161
	v_lshlrev_b32_e32 v2, 16, v156
	v_and_b32_e32 v3, 0xffff0000, v156
	v_pk_mul_f32 v[2:3], v[2:3], v[160:161]
	v_pk_mul_f32 v[120:121], v[120:121], v[2:3]
	v_lshlrev_b32_e32 v160, 16, v187
	v_and_b32_e32 v161, 0xffff0000, v187
	v_rcp_f32_e32 v160, v160
	v_rcp_f32_e32 v161, v161
	v_lshlrev_b32_e32 v2, 16, v157
	v_and_b32_e32 v3, 0xffff0000, v157
	v_pk_mul_f32 v[2:3], v[2:3], v[160:161]
	v_pk_mul_f32 v[122:123], v[122:123], v[2:3]
	v_lshlrev_b32_e32 v160, 16, v188
	v_and_b32_e32 v161, 0xffff0000, v188
	v_rcp_f32_e32 v160, v160
	v_rcp_f32_e32 v161, v161
	v_lshlrev_b32_e32 v2, 16, v158
	v_and_b32_e32 v3, 0xffff0000, v158
	v_pk_mul_f32 v[2:3], v[2:3], v[160:161]
	v_pk_mul_f32 v[116:117], v[116:117], v[2:3]
	v_lshlrev_b32_e32 v160, 16, v189
	v_and_b32_e32 v161, 0xffff0000, v189
	v_rcp_f32_e32 v160, v160
	v_rcp_f32_e32 v161, v161
	v_lshlrev_b32_e32 v2, 16, v159
	v_and_b32_e32 v3, 0xffff0000, v159
	v_pk_mul_f32 v[2:3], v[2:3], v[160:161]
	v_pk_mul_f32 v[118:119], v[118:119], v[2:3]
	v_add_u32_e32 v175, 0x2e0000, v1
	global_load_dwordx4 v[156:159], v175, s[46:47] offset:256 nt
	global_load_dwordx4 v[186:189], v175, s[100:101] offset:256 nt
	s_waitcnt vmcnt(14)
	v_lshlrev_b32_e32 v160, 16, v194
	v_and_b32_e32 v161, 0xffff0000, v194
	v_rcp_f32_e32 v160, v160
	v_rcp_f32_e32 v161, v161
	v_lshlrev_b32_e32 v2, 16, v190
	v_and_b32_e32 v3, 0xffff0000, v190
	v_pk_mul_f32 v[2:3], v[2:3], v[160:161]
	v_pk_mul_f32 v[112:113], v[112:113], v[2:3]
	v_lshlrev_b32_e32 v160, 16, v195
	v_and_b32_e32 v161, 0xffff0000, v195
	v_rcp_f32_e32 v160, v160
	v_rcp_f32_e32 v161, v161
	v_lshlrev_b32_e32 v2, 16, v191
	v_and_b32_e32 v3, 0xffff0000, v191
	v_pk_mul_f32 v[2:3], v[2:3], v[160:161]
	v_pk_mul_f32 v[114:115], v[114:115], v[2:3]
	v_lshlrev_b32_e32 v160, 16, v196
	v_and_b32_e32 v161, 0xffff0000, v196
	v_rcp_f32_e32 v160, v160
	v_rcp_f32_e32 v161, v161
	v_lshlrev_b32_e32 v2, 16, v192
	v_and_b32_e32 v3, 0xffff0000, v192
	v_pk_mul_f32 v[2:3], v[2:3], v[160:161]
	v_pk_mul_f32 v[108:109], v[108:109], v[2:3]
	v_lshlrev_b32_e32 v160, 16, v197
	v_and_b32_e32 v161, 0xffff0000, v197
	v_rcp_f32_e32 v160, v160
	v_rcp_f32_e32 v161, v161
	v_lshlrev_b32_e32 v2, 16, v193
	v_and_b32_e32 v3, 0xffff0000, v193
	v_pk_mul_f32 v[2:3], v[2:3], v[160:161]
	v_pk_mul_f32 v[110:111], v[110:111], v[2:3]
	v_add_u32_e32 v175, 0x33c000, v1
	global_load_dwordx4 v[190:193], v175, s[46:47] offset:0 nt
	global_load_dwordx4 v[194:197], v175, s[100:101] offset:0 nt
	s_waitcnt vmcnt(14)
;     __device__ __forceinline__ void rescale(f32x4 (&acc)[2][2][4][2], const Unit& u, int seg, int wr, int wc, int fr, int fq) const {
;     ...
;                 const bf16_t* gp = Gt + (size_t)(row0 + ai * HALF + m * 16) * NP + seg * 2048 + col0;
; #pragma unroll
;                 for (int bj = 0; bj < 2; ++bj) {
;                     const u32x4 ga = *(const u32x4*)(gp + bj * HALF), gb = *(const u32x4*)(gp + bj * HALF + 2048);
;                     float fa[8], fb[8]; unpack8(ga, fa); unpack8(gb, fb);
; #pragma unroll
;                     for (int j = 0; j < 4; ++j) { acc[ai][bj][m][0][j] *= __fdividef(fa[j], fb[j]); acc[ai][bj][m][1][j] *= __fdividef(fa[4 + j], fb[4 + j]); }
;                     asm volatile("" : "+v"(acc[ai][bj][m][0]), "+v"(acc[ai][bj][m][1]) :: "memory");
;                 }
	v_lshlrev_b32_e32 v160, 16, v202
	v_and_b32_e32 v161, 0xffff0000, v202
	v_rcp_f32_e32 v160, v160
	v_rcp_f32_e32 v161, v161
	v_lshlrev_b32_e32 v2, 16, v198
	v_and_b32_e32 v3, 0xffff0000, v198
	v_pk_mul_f32 v[2:3], v[2:3], v[160:161]
	v_pk_mul_f32 v[104:105], v[104:105], v[2:3]
	v_lshlrev_b32_e32 v160, 16, v203
	v_and_b32_e32 v161, 0xffff0000, v203
	v_rcp_f32_e32 v160, v160
	v_rcp_f32_e32 v161, v161
	v_lshlrev_b32_e32 v2, 16, v199
	v_and_b32_e32 v3, 0xffff0000, v199
	v_pk_mul_f32 v[2:3], v[2:3], v[160:161]
	v_pk_mul_f32 v[106:107], v[106:107], v[2:3]
	v_lshlrev_b32_e32 v160, 16, v204
	v_and_b32_e32 v161, 0xffff0000, v204
	v_rcp_f32_e32 v160, v160
	v_rcp_f32_e32 v161, v161
	v_lshlrev_b32_e32 v2, 16, v200
	v_and_b32_e32 v3, 0xffff0000, v200
	v_pk_mul_f32 v[2:3], v[2:3], v[160:161]
	v_pk_mul_f32 v[100:101], v[100:101], v[2:3]
	v_lshlrev_b32_e32 v160, 16, v205
	v_and_b32_e32 v161, 0xffff0000, v205
	v_rcp_f32_e32 v160, v160
	v_rcp_f32_e32 v161, v161
	v_lshlrev_b32_e32 v2, 16, v201
	v_and_b32_e32 v3, 0xffff0000, v201
	v_pk_mul_f32 v[2:3], v[2:3], v[160:161]
	v_pk_mul_f32 v[102:103], v[102:103], v[2:3]
	v_add_u32_e32 v175, 0x33c000, v1
	global_load_dwordx4 v[198:201], v175, s[46:47] offset:256 nt
	global_load_dwordx4 v[202:205], v175, s[100:101] offset:256 nt
	s_waitcnt vmcnt(14)
	v_lshlrev_b32_e32 v160, 16, v222
	v_and_b32_e32 v161, 0xffff0000, v222
	v_rcp_f32_e32 v160, v160
	v_rcp_f32_e32 v161, v161
	v_lshlrev_b32_e32 v2, 16, v206
	v_and_b32_e32 v3, 0xffff0000, v206
	v_pk_mul_f32 v[2:3], v[2:3], v[160:161]
	v_pk_mul_f32 v[96:97], v[96:97], v[2:3]
	v_lshlrev_b32_e32 v160, 16, v223
	v_and_b32_e32 v161, 0xffff0000, v223
	v_rcp_f32_e32 v160, v160
	v_rcp_f32_e32 v161, v161
	v_lshlrev_b32_e32 v2, 16, v207
	v_and_b32_e32 v3, 0xffff0000, v207
	v_pk_mul_f32 v[2:3], v[2:3], v[160:161]
	v_pk_mul_f32 v[98:99], v[98:99], v[2:3]
	v_lshlrev_b32_e32 v160, 16, v224
	v_and_b32_e32 v161, 0xffff0000, v224
	v_rcp_f32_e32 v160, v160
	v_rcp_f32_e32 v161, v161
	v_lshlrev_b32_e32 v2, 16, v208
	v_and_b32_e32 v3, 0xffff0000, v208
	v_pk_mul_f32 v[2:3], v[2:3], v[160:161]
	v_pk_mul_f32 v[92:93], v[92:93], v[2:3]
	v_lshlrev_b32_e32 v160, 16, v225
	v_and_b32_e32 v161, 0xffff0000, v225
	v_rcp_f32_e32 v160, v160
	v_rcp_f32_e32 v161, v161
	v_lshlrev_b32_e32 v2, 16, v209
	v_and_b32_e32 v3, 0xffff0000, v209
	v_pk_mul_f32 v[2:3], v[2:3], v[160:161]
	v_pk_mul_f32 v[94:95], v[94:95], v[2:3]
	v_add_u32_e32 v175, 0x398000, v1
	global_load_dwordx4 v[206:209], v175, s[46:47] offset:0 nt
	global_load_dwordx4 v[222:225], v175, s[100:101] offset:0 nt
	s_waitcnt vmcnt(14)
	v_lshlrev_b32_e32 v160, 16, v230
	v_and_b32_e32 v161, 0xffff0000, v230
	v_rcp_f32_e32 v160, v160
	v_rcp_f32_e32 v161, v161
	v_lshlrev_b32_e32 v2, 16, v226
	v_and_b32_e32 v3, 0xffff0000, v226
	v_pk_mul_f32 v[2:3], v[2:3], v[160:161]
	v_pk_mul_f32 v[88:89], v[88:89], v[2:3]
	v_lshlrev_b32_e32 v160, 16, v231
	v_and_b32_e32 v161, 0xffff0000, v231
	v_rcp_f32_e32 v160, v160
	v_rcp_f32_e32 v161, v161
	v_lshlrev_b32_e32 v2, 16, v227
	v_and_b32_e32 v3, 0xffff0000, v227
	v_pk_mul_f32 v[2:3], v[2:3], v[160:161]
	v_pk_mul_f32 v[90:91], v[90:91], v[2:3]
	v_lshlrev_b32_e32 v160, 16, v232
	v_and_b32_e32 v161, 0xffff0000, v232
	v_rcp_f32_e32 v160, v160
	v_rcp_f32_e32 v161, v161
	v_lshlrev_b32_e32 v2, 16, v228
	v_and_b32_e32 v3, 0xffff0000, v228
	v_pk_mul_f32 v[2:3], v[2:3], v[160:161]
	v_pk_mul_f32 v[84:85], v[84:85], v[2:3]
	v_lshlrev_b32_e32 v160, 16, v233
	v_and_b32_e32 v161, 0xffff0000, v233
	v_rcp_f32_e32 v160, v160
	v_rcp_f32_e32 v161, v161
	v_lshlrev_b32_e32 v2, 16, v229
	v_and_b32_e32 v3, 0xffff0000, v229
	v_pk_mul_f32 v[2:3], v[2:3], v[160:161]
	v_pk_mul_f32 v[86:87], v[86:87], v[2:3]
	v_add_u32_e32 v175, 0x398000, v1
	global_load_dwordx4 v[226:229], v175, s[46:47] offset:256 nt
	global_load_dwordx4 v[230:233], v175, s[100:101] offset:256 nt
	s_waitcnt vmcnt(14)
	v_lshlrev_b32_e32 v160, 16, v238
	v_and_b32_e32 v161, 0xffff0000, v238
	v_rcp_f32_e32 v160, v160
	v_rcp_f32_e32 v161, v161
	v_lshlrev_b32_e32 v2, 16, v234
	v_and_b32_e32 v3, 0xffff0000, v234
	v_pk_mul_f32 v[2:3], v[2:3], v[160:161]
	v_pk_mul_f32 v[80:81], v[80:81], v[2:3]
	v_lshlrev_b32_e32 v160, 16, v239
	v_and_b32_e32 v161, 0xffff0000, v239
	v_rcp_f32_e32 v160, v160
	v_rcp_f32_e32 v161, v161
	v_lshlrev_b32_e32 v2, 16, v235
	v_and_b32_e32 v3, 0xffff0000, v235
	v_pk_mul_f32 v[2:3], v[2:3], v[160:161]
	v_pk_mul_f32 v[82:83], v[82:83], v[2:3]
	v_lshlrev_b32_e32 v160, 16, v240
	v_and_b32_e32 v161, 0xffff0000, v240
	v_rcp_f32_e32 v160, v160
	v_rcp_f32_e32 v161, v161
	v_lshlrev_b32_e32 v2, 16, v236
	v_and_b32_e32 v3, 0xffff0000, v236
	v_pk_mul_f32 v[2:3], v[2:3], v[160:161]
	v_pk_mul_f32 v[76:77], v[76:77], v[2:3]
	v_lshlrev_b32_e32 v160, 16, v241
	v_and_b32_e32 v161, 0xffff0000, v241
	v_rcp_f32_e32 v160, v160
	v_rcp_f32_e32 v161, v161
	v_lshlrev_b32_e32 v2, 16, v237
	v_and_b32_e32 v3, 0xffff0000, v237
	v_pk_mul_f32 v[2:3], v[2:3], v[160:161]
	v_pk_mul_f32 v[78:79], v[78:79], v[2:3]
	v_add_u32_e32 v175, 0x3f4000, v1
	global_load_dwordx4 v[234:237], v175, s[46:47] offset:0 nt
	global_load_dwordx4 v[238:241], v175, s[100:101] offset:0 nt
	s_waitcnt vmcnt(14)
;     __device__ __forceinline__ void rescale(f32x4 (&acc)[2][2][4][2], const Unit& u, int seg, int wr, int wc, int fr, int fq) const {
;     ...
;                 const bf16_t* gp = Gt + (size_t)(row0 + ai * HALF + m * 16) * NP + seg * 2048 + col0;
; #pragma unroll
;                 for (int bj = 0; bj < 2; ++bj) {
;                     const u32x4 ga = *(const u32x4*)(gp + bj * HALF), gb = *(const u32x4*)(gp + bj * HALF + 2048);
;                     float fa[8], fb[8]; unpack8(ga, fa); unpack8(gb, fb);
; #pragma unroll
;                     for (int j = 0; j < 4; ++j) { acc[ai][bj][m][0][j] *= __fdividef(fa[j], fb[j]); acc[ai][bj][m][1][j] *= __fdividef(fa[4 + j], fb[4 + j]); }
;                     asm volatile("" : "+v"(acc[ai][bj][m][0]), "+v"(acc[ai][bj][m][1]) :: "memory");
;                 }
	v_lshlrev_b32_e32 v160, 16, v246
	v_and_b32_e32 v161, 0xffff0000, v246
	v_rcp_f32_e32 v160, v160
	v_rcp_f32_e32 v161, v161
	v_lshlrev_b32_e32 v2, 16, v242
	v_and_b32_e32 v3, 0xffff0000, v242
	v_pk_mul_f32 v[2:3], v[2:3], v[160:161]
	v_pk_mul_f32 v[72:73], v[72:73], v[2:3]
	v_lshlrev_b32_e32 v160, 16, v247
	v_and_b32_e32 v161, 0xffff0000, v247
	v_rcp_f32_e32 v160, v160
	v_rcp_f32_e32 v161, v161
	v_lshlrev_b32_e32 v2, 16, v243
	v_and_b32_e32 v3, 0xffff0000, v243
	v_pk_mul_f32 v[2:3], v[2:3], v[160:161]
	v_pk_mul_f32 v[74:75], v[74:75], v[2:3]
	v_lshlrev_b32_e32 v160, 16, v248
	v_and_b32_e32 v161, 0xffff0000, v248
	v_rcp_f32_e32 v160, v160
	v_rcp_f32_e32 v161, v161
	v_lshlrev_b32_e32 v2, 16, v244
	v_and_b32_e32 v3, 0xffff0000, v244
	v_pk_mul_f32 v[2:3], v[2:3], v[160:161]
	v_pk_mul_f32 v[68:69], v[68:69], v[2:3]
	v_lshlrev_b32_e32 v160, 16, v249
	v_and_b32_e32 v161, 0xffff0000, v249
	v_rcp_f32_e32 v160, v160
	v_rcp_f32_e32 v161, v161
	v_lshlrev_b32_e32 v2, 16, v245
	v_and_b32_e32 v3, 0xffff0000, v245
	v_pk_mul_f32 v[2:3], v[2:3], v[160:161]
	v_pk_mul_f32 v[70:71], v[70:71], v[2:3]
	v_add_u32_e32 v175, 0x3f4000, v1
	global_load_dwordx4 v[242:245], v175, s[46:47] offset:256 nt
	global_load_dwordx4 v[246:249], v175, s[100:101] offset:256 nt
	s_waitcnt vmcnt(14)
	v_lshlrev_b32_e32 v160, 16, v136
	v_and_b32_e32 v161, 0xffff0000, v136
	v_rcp_f32_e32 v160, v160
	v_rcp_f32_e32 v161, v161
	v_lshlrev_b32_e32 v2, 16, v132
	v_and_b32_e32 v3, 0xffff0000, v132
	v_pk_mul_f32 v[2:3], v[2:3], v[160:161]
	v_pk_mul_f32 v[64:65], v[64:65], v[2:3]
	v_lshlrev_b32_e32 v160, 16, v137
	v_and_b32_e32 v161, 0xffff0000, v137
	v_rcp_f32_e32 v160, v160
	v_rcp_f32_e32 v161, v161
	v_lshlrev_b32_e32 v2, 16, v133
	v_and_b32_e32 v3, 0xffff0000, v133
	v_pk_mul_f32 v[2:3], v[2:3], v[160:161]
	v_pk_mul_f32 v[66:67], v[66:67], v[2:3]
	v_lshlrev_b32_e32 v160, 16, v138
	v_and_b32_e32 v161, 0xffff0000, v138
	v_rcp_f32_e32 v160, v160
	v_rcp_f32_e32 v161, v161
	v_lshlrev_b32_e32 v2, 16, v134
	v_and_b32_e32 v3, 0xffff0000, v134
	v_pk_mul_f32 v[2:3], v[2:3], v[160:161]
	v_pk_mul_f32 v[60:61], v[60:61], v[2:3]
	v_lshlrev_b32_e32 v160, 16, v139
	v_and_b32_e32 v161, 0xffff0000, v139
	v_rcp_f32_e32 v160, v160
	v_rcp_f32_e32 v161, v161
	v_lshlrev_b32_e32 v2, 16, v135
	v_and_b32_e32 v3, 0xffff0000, v135
	v_pk_mul_f32 v[2:3], v[2:3], v[160:161]
	v_pk_mul_f32 v[62:63], v[62:63], v[2:3]
	s_waitcnt vmcnt(12)
	v_lshlrev_b32_e32 v160, 16, v186
	v_and_b32_e32 v161, 0xffff0000, v186
	v_rcp_f32_e32 v160, v160
	v_rcp_f32_e32 v161, v161
	v_lshlrev_b32_e32 v2, 16, v156
	v_and_b32_e32 v3, 0xffff0000, v156
	v_pk_mul_f32 v[2:3], v[2:3], v[160:161]
	v_pk_mul_f32 v[56:57], v[56:57], v[2:3]
	v_lshlrev_b32_e32 v160, 16, v187
	v_and_b32_e32 v161, 0xffff0000, v187
	v_rcp_f32_e32 v160, v160
	v_rcp_f32_e32 v161, v161
	v_lshlrev_b32_e32 v2, 16, v157
	v_and_b32_e32 v3, 0xffff0000, v157
	v_pk_mul_f32 v[2:3], v[2:3], v[160:161]
	v_pk_mul_f32 v[58:59], v[58:59], v[2:3]
	v_lshlrev_b32_e32 v160, 16, v188
	v_and_b32_e32 v161, 0xffff0000, v188
	v_rcp_f32_e32 v160, v160
	v_rcp_f32_e32 v161, v161
	v_lshlrev_b32_e32 v2, 16, v158
	v_and_b32_e32 v3, 0xffff0000, v158
	v_pk_mul_f32 v[2:3], v[2:3], v[160:161]
	v_pk_mul_f32 v[52:53], v[52:53], v[2:3]
	v_lshlrev_b32_e32 v160, 16, v189
	v_and_b32_e32 v161, 0xffff0000, v189
	v_rcp_f32_e32 v160, v160
	v_rcp_f32_e32 v161, v161
	v_lshlrev_b32_e32 v2, 16, v159
	v_and_b32_e32 v3, 0xffff0000, v159
	v_pk_mul_f32 v[2:3], v[2:3], v[160:161]
	v_pk_mul_f32 v[54:55], v[54:55], v[2:3]
	s_waitcnt vmcnt(10)
	v_lshlrev_b32_e32 v160, 16, v194
	v_and_b32_e32 v161, 0xffff0000, v194
	v_rcp_f32_e32 v160, v160
	v_rcp_f32_e32 v161, v161
	v_lshlrev_b32_e32 v2, 16, v190
	v_and_b32_e32 v3, 0xffff0000, v190
	v_pk_mul_f32 v[2:3], v[2:3], v[160:161]
	v_pk_mul_f32 v[48:49], v[48:49], v[2:3]
	v_lshlrev_b32_e32 v160, 16, v195
	v_and_b32_e32 v161, 0xffff0000, v195
	v_rcp_f32_e32 v160, v160
	v_rcp_f32_e32 v161, v161
	v_lshlrev_b32_e32 v2, 16, v191
	v_and_b32_e32 v3, 0xffff0000, v191
	v_pk_mul_f32 v[2:3], v[2:3], v[160:161]
	v_pk_mul_f32 v[50:51], v[50:51], v[2:3]
	v_lshlrev_b32_e32 v160, 16, v196
	v_and_b32_e32 v161, 0xffff0000, v196
	v_rcp_f32_e32 v160, v160
	v_rcp_f32_e32 v161, v161
	v_lshlrev_b32_e32 v2, 16, v192
	v_and_b32_e32 v3, 0xffff0000, v192
	v_pk_mul_f32 v[2:3], v[2:3], v[160:161]
	v_pk_mul_f32 v[44:45], v[44:45], v[2:3]
	v_lshlrev_b32_e32 v160, 16, v197
	v_and_b32_e32 v161, 0xffff0000, v197
	v_rcp_f32_e32 v160, v160
	v_rcp_f32_e32 v161, v161
	v_lshlrev_b32_e32 v2, 16, v193
	v_and_b32_e32 v3, 0xffff0000, v193
	v_pk_mul_f32 v[2:3], v[2:3], v[160:161]
	v_pk_mul_f32 v[46:47], v[46:47], v[2:3]
	s_waitcnt vmcnt(8)
;     __device__ __forceinline__ void rescale(f32x4 (&acc)[2][2][4][2], const Unit& u, int seg, int wr, int wc, int fr, int fq) const {
;     ...
;                     const u32x4 ga = *(const u32x4*)(gp + bj * HALF), gb = *(const u32x4*)(gp + bj * HALF + 2048);
;                     float fa[8], fb[8]; unpack8(ga, fa); unpack8(gb, fb);
; #pragma unroll
;                     for (int j = 0; j < 4; ++j) { acc[ai][bj][m][0][j] *= __fdividef(fa[j], fb[j]); acc[ai][bj][m][1][j] *= __fdividef(fa[4 + j], fb[4 + j]); }
;                     asm volatile("" : "+v"(acc[ai][bj][m][0]), "+v"(acc[ai][bj][m][1]) :: "memory");
;                 }
	v_lshlrev_b32_e32 v160, 16, v202
	v_and_b32_e32 v161, 0xffff0000, v202
	v_rcp_f32_e32 v160, v160
	v_rcp_f32_e32 v161, v161
	v_lshlrev_b32_e32 v2, 16, v198
	v_and_b32_e32 v3, 0xffff0000, v198
	v_pk_mul_f32 v[2:3], v[2:3], v[160:161]
	v_pk_mul_f32 v[40:41], v[40:41], v[2:3]
	v_lshlrev_b32_e32 v160, 16, v203
	v_and_b32_e32 v161, 0xffff0000, v203
	v_rcp_f32_e32 v160, v160
	v_rcp_f32_e32 v161, v161
	v_lshlrev_b32_e32 v2, 16, v199
	v_and_b32_e32 v3, 0xffff0000, v199
	v_pk_mul_f32 v[2:3], v[2:3], v[160:161]
	v_pk_mul_f32 v[42:43], v[42:43], v[2:3]
	v_lshlrev_b32_e32 v160, 16, v204
	v_and_b32_e32 v161, 0xffff0000, v204
	v_rcp_f32_e32 v160, v160
	v_rcp_f32_e32 v161, v161
	v_lshlrev_b32_e32 v2, 16, v200
	v_and_b32_e32 v3, 0xffff0000, v200
	v_pk_mul_f32 v[2:3], v[2:3], v[160:161]
	v_pk_mul_f32 v[36:37], v[36:37], v[2:3]
	v_lshlrev_b32_e32 v160, 16, v205
	v_and_b32_e32 v161, 0xffff0000, v205
	v_rcp_f32_e32 v160, v160
	v_rcp_f32_e32 v161, v161
	v_lshlrev_b32_e32 v2, 16, v201
	v_and_b32_e32 v3, 0xffff0000, v201
	v_pk_mul_f32 v[2:3], v[2:3], v[160:161]
	v_pk_mul_f32 v[38:39], v[38:39], v[2:3]
	s_waitcnt vmcnt(6)
	v_lshlrev_b32_e32 v160, 16, v222
	v_and_b32_e32 v161, 0xffff0000, v222
	v_rcp_f32_e32 v160, v160
	v_rcp_f32_e32 v161, v161
	v_lshlrev_b32_e32 v2, 16, v206
	v_and_b32_e32 v3, 0xffff0000, v206
	v_pk_mul_f32 v[2:3], v[2:3], v[160:161]
	v_pk_mul_f32 v[32:33], v[32:33], v[2:3]
	v_lshlrev_b32_e32 v160, 16, v223
	v_and_b32_e32 v161, 0xffff0000, v223
	v_rcp_f32_e32 v160, v160
	v_rcp_f32_e32 v161, v161
	v_lshlrev_b32_e32 v2, 16, v207
	v_and_b32_e32 v3, 0xffff0000, v207
	v_pk_mul_f32 v[2:3], v[2:3], v[160:161]
	v_pk_mul_f32 v[34:35], v[34:35], v[2:3]
	v_lshlrev_b32_e32 v160, 16, v224
	v_and_b32_e32 v161, 0xffff0000, v224
	v_rcp_f32_e32 v160, v160
	v_rcp_f32_e32 v161, v161
	v_lshlrev_b32_e32 v2, 16, v208
	v_and_b32_e32 v3, 0xffff0000, v208
	v_pk_mul_f32 v[2:3], v[2:3], v[160:161]
	v_pk_mul_f32 v[28:29], v[28:29], v[2:3]
	v_lshlrev_b32_e32 v160, 16, v225
	v_and_b32_e32 v161, 0xffff0000, v225
	v_rcp_f32_e32 v160, v160
	v_rcp_f32_e32 v161, v161
	v_lshlrev_b32_e32 v2, 16, v209
	v_and_b32_e32 v3, 0xffff0000, v209
	v_pk_mul_f32 v[2:3], v[2:3], v[160:161]
	v_pk_mul_f32 v[30:31], v[30:31], v[2:3]
	s_waitcnt vmcnt(4)
	v_lshlrev_b32_e32 v160, 16, v230
	v_and_b32_e32 v161, 0xffff0000, v230
	v_rcp_f32_e32 v160, v160
	v_rcp_f32_e32 v161, v161
	v_lshlrev_b32_e32 v2, 16, v226
	v_and_b32_e32 v3, 0xffff0000, v226
	v_pk_mul_f32 v[2:3], v[2:3], v[160:161]
	v_pk_mul_f32 v[24:25], v[24:25], v[2:3]
	v_lshlrev_b32_e32 v160, 16, v231
	v_and_b32_e32 v161, 0xffff0000, v231
	v_rcp_f32_e32 v160, v160
	v_rcp_f32_e32 v161, v161
	v_lshlrev_b32_e32 v2, 16, v227
	v_and_b32_e32 v3, 0xffff0000, v227
	v_pk_mul_f32 v[2:3], v[2:3], v[160:161]
	v_pk_mul_f32 v[26:27], v[26:27], v[2:3]
	v_lshlrev_b32_e32 v160, 16, v232
	v_and_b32_e32 v161, 0xffff0000, v232
	v_rcp_f32_e32 v160, v160
	v_rcp_f32_e32 v161, v161
	v_lshlrev_b32_e32 v2, 16, v228
	v_and_b32_e32 v3, 0xffff0000, v228
	v_pk_mul_f32 v[2:3], v[2:3], v[160:161]
	v_pk_mul_f32 v[20:21], v[20:21], v[2:3]
	v_lshlrev_b32_e32 v160, 16, v233
	v_and_b32_e32 v161, 0xffff0000, v233
	v_rcp_f32_e32 v160, v160
	v_rcp_f32_e32 v161, v161
	v_lshlrev_b32_e32 v2, 16, v229
	v_and_b32_e32 v3, 0xffff0000, v229
	v_pk_mul_f32 v[2:3], v[2:3], v[160:161]
	v_pk_mul_f32 v[22:23], v[22:23], v[2:3]
	s_waitcnt vmcnt(2)
	v_lshlrev_b32_e32 v160, 16, v238
	v_and_b32_e32 v161, 0xffff0000, v238
	v_rcp_f32_e32 v160, v160
	v_rcp_f32_e32 v161, v161
	v_lshlrev_b32_e32 v2, 16, v234
	v_and_b32_e32 v3, 0xffff0000, v234
	v_pk_mul_f32 v[2:3], v[2:3], v[160:161]
	v_pk_mul_f32 v[16:17], v[16:17], v[2:3]
	v_lshlrev_b32_e32 v160, 16, v239
	v_and_b32_e32 v161, 0xffff0000, v239
	v_rcp_f32_e32 v160, v160
	v_rcp_f32_e32 v161, v161
	v_lshlrev_b32_e32 v2, 16, v235
	v_and_b32_e32 v3, 0xffff0000, v235
	v_pk_mul_f32 v[2:3], v[2:3], v[160:161]
	v_pk_mul_f32 v[18:19], v[18:19], v[2:3]
	v_lshlrev_b32_e32 v160, 16, v240
	v_and_b32_e32 v161, 0xffff0000, v240
	v_rcp_f32_e32 v160, v160
	v_rcp_f32_e32 v161, v161
	v_lshlrev_b32_e32 v2, 16, v236
	v_and_b32_e32 v3, 0xffff0000, v236
	v_pk_mul_f32 v[2:3], v[2:3], v[160:161]
	v_pk_mul_f32 v[12:13], v[12:13], v[2:3]
	v_lshlrev_b32_e32 v160, 16, v241
	v_and_b32_e32 v161, 0xffff0000, v241
	v_rcp_f32_e32 v160, v160
	v_rcp_f32_e32 v161, v161
	v_lshlrev_b32_e32 v2, 16, v237
	v_and_b32_e32 v3, 0xffff0000, v237
	v_pk_mul_f32 v[2:3], v[2:3], v[160:161]
	v_pk_mul_f32 v[14:15], v[14:15], v[2:3]
	s_waitcnt vmcnt(0)
	v_lshlrev_b32_e32 v160, 16, v246
	v_and_b32_e32 v161, 0xffff0000, v246
	v_rcp_f32_e32 v160, v160
	v_rcp_f32_e32 v161, v161
	v_lshlrev_b32_e32 v2, 16, v242
	v_and_b32_e32 v3, 0xffff0000, v242
	v_pk_mul_f32 v[2:3], v[2:3], v[160:161]
	v_pk_mul_f32 v[8:9], v[8:9], v[2:3]
	v_lshlrev_b32_e32 v160, 16, v247
	v_and_b32_e32 v161, 0xffff0000, v247
	v_rcp_f32_e32 v160, v160
	v_rcp_f32_e32 v161, v161
	v_lshlrev_b32_e32 v2, 16, v243
	v_and_b32_e32 v3, 0xffff0000, v243
	v_pk_mul_f32 v[2:3], v[2:3], v[160:161]
	v_pk_mul_f32 v[10:11], v[10:11], v[2:3]
	v_lshlrev_b32_e32 v160, 16, v248
	v_and_b32_e32 v161, 0xffff0000, v248
	v_rcp_f32_e32 v160, v160
	v_rcp_f32_e32 v161, v161
	v_lshlrev_b32_e32 v2, 16, v244
	v_and_b32_e32 v3, 0xffff0000, v244
	v_pk_mul_f32 v[2:3], v[2:3], v[160:161]
	v_pk_mul_f32 v[4:5], v[4:5], v[2:3]
	v_lshlrev_b32_e32 v160, 16, v249
	v_and_b32_e32 v161, 0xffff0000, v249
	v_rcp_f32_e32 v160, v160
	v_rcp_f32_e32 v161, v161
	v_lshlrev_b32_e32 v2, 16, v245
	v_and_b32_e32 v3, 0xffff0000, v245
	v_pk_mul_f32 v[2:3], v[2:3], v[160:161]
	v_pk_mul_f32 v[6:7], v[6:7], v[2:3]

; __device__ __forceinline__ unsigned cvt_pk_bf16(float lo, float hi) { unsigned r; asm volatile("v_cvt_pk_bf16_f32 %0, %1, %2" : "=v"(r) : "v"(lo), "v"(hi)); return r; }
;     __device__ __forceinline__ void operator()(f32x4 (&acc)[2][2][4][2], const Unit& u, int wr, int wc, int fr, int fq) const {
;         int t2_ = threadIdx.x; asm volatile("" : "+v"(t2_)); (void)wr; (void)wc; (void)fr; (void)fq;
;         const int row0 = u.pm * BM + ((t2_ >> 8) & 1) * 64 + (t2_ & 15), col0 = u.pn * BM + ((t2_ >> 6) & 3) * 32 + 8 * ((t2_ >> 4) & 3);
; #pragma unroll
;         for (int ai = 0; ai < 2; ++ai)
; #pragma unroll
;             for (int m = 0; m < 4; ++m) {
;                 const size_t r = (size_t)(row0 + ai * HALF + m * 16);
; #pragma unroll
;                 for (int bj = 0; bj < 2; ++bj) {
;                     const u32x4 gc = *(const u32x4*)(Gt + r * NP + 4096 + col0 + bj * HALF);
;                     float fc[8]; unpack8(gc, fc);
;                     f32x4 v0 = acc[ai][bj][m][0], v1 = acc[ai][bj][m][1];
;                     u32x4 w; w.x = cvt_pk_bf16(v0[0] * fc[0], v0[1] * fc[1]); w.y = cvt_pk_bf16(v0[2] * fc[2], v0[3] * fc[3]);
;                     w.z = cvt_pk_bf16(v1[0] * fc[4], v1[1] * fc[5]); w.w = cvt_pk_bf16(v1[2] * fc[6], v1[3] * fc[7]);
;                     *(u32x4*)(O + r * DM + col0 + bj * HALF) = w;
;                     asm volatile("" ::: "memory");
;                 }
;             }
;     }
.LBB0_886:
	v_mov_b32_e32 v2, v210
	v_lshrrev_b32_e32 v1, 2, v2
	v_and_b32_e32 v3, 15, v2
	v_lshrrev_b32_e32 v2, 1, v2
	v_and_b32_e32 v1, 64, v1
	v_and_b32_e32 v2, 0x78, v2
	v_or3_b32 v1, v3, v1, s9
	v_or_b32_e32 v2, s51, v2
	s_mov_b64 s[36:37], -1
	v_lshlrev_b32_e32 v3, 12, v1
	v_mul_u32_u24_e32 v1, 0x5c00, v1
	v_lshlrev_b32_e32 v2, 1, v2
	v_add3_u32 v1, v1, v2, s79
	v_add_u32_e32 v2, v3, v2
	global_load_dwordx4 v[132:135], v1, s[46:47] offset:0 nt
	global_load_dwordx4 v[136:139], v1, s[46:47] offset:256 nt
	v_add_u32_e32 v152, 0x5c000, v1
	global_load_dwordx4 v[156:159], v152, s[46:47] offset:0 nt
	global_load_dwordx4 v[186:189], v152, s[46:47] offset:256 nt
	v_add_u32_e32 v153, 0xb8000, v1
	global_load_dwordx4 v[190:193], v153, s[46:47] offset:0 nt
	global_load_dwordx4 v[194:197], v153, s[46:47] offset:256 nt
	v_add_u32_e32 v154, 0x114000, v1
	global_load_dwordx4 v[198:201], v154, s[46:47] offset:0 nt
	global_load_dwordx4 v[202:205], v154, s[46:47] offset:256 nt
	v_add_u32_e32 v3, 0x2e0000, v1
	global_load_dwordx4 v[206:209], v3, s[46:47] offset:0 nt
	global_load_dwordx4 v[222:225], v3, s[46:47] offset:256 nt
	v_add_u32_e32 v152, 0x33c000, v1
	global_load_dwordx4 v[226:229], v152, s[46:47] offset:0 nt
	global_load_dwordx4 v[230:233], v152, s[46:47] offset:256 nt
	v_add_u32_e32 v153, 0x398000, v1
	global_load_dwordx4 v[234:237], v153, s[46:47] offset:0 nt
	global_load_dwordx4 v[238:241], v153, s[46:47] offset:256 nt
	v_add_u32_e32 v154, 0x3f4000, v1
	global_load_dwordx4 v[242:245], v154, s[46:47] offset:0 nt
	global_load_dwordx4 v[246:249], v154, s[46:47] offset:256 nt
	s_waitcnt vmcnt(15)
	v_lshlrev_b32_e32 v152, 16, v132
	v_and_b32_e32 v153, 0xffff0000, v132
	v_pk_mul_f32 v[128:129], v[128:129], v[152:153]
	v_lshlrev_b32_e32 v152, 16, v133
	v_and_b32_e32 v153, 0xffff0000, v133
	v_pk_mul_f32 v[130:131], v[130:131], v[152:153]
	v_lshlrev_b32_e32 v152, 16, v134
	v_and_b32_e32 v153, 0xffff0000, v134
	v_pk_mul_f32 v[124:125], v[124:125], v[152:153]
	v_lshlrev_b32_e32 v152, 16, v135
	v_and_b32_e32 v153, 0xffff0000, v135
	v_pk_mul_f32 v[126:127], v[126:127], v[152:153]
	v_cvt_pk_bf16_f32 v128, v128, v129
	v_cvt_pk_bf16_f32 v129, v130, v131
	v_cvt_pk_bf16_f32 v130, v124, v125
	v_cvt_pk_bf16_f32 v131, v126, v127
	global_store_dwordx4 v2, v[128:131], s[44:45] offset:0
	s_waitcnt vmcnt(15)
	v_lshlrev_b32_e32 v152, 16, v136
	v_and_b32_e32 v153, 0xffff0000, v136
	v_pk_mul_f32 v[120:121], v[120:121], v[152:153]
	v_lshlrev_b32_e32 v152, 16, v137
	v_and_b32_e32 v153, 0xffff0000, v137
	v_pk_mul_f32 v[122:123], v[122:123], v[152:153]
	v_lshlrev_b32_e32 v152, 16, v138
	v_and_b32_e32 v153, 0xffff0000, v138
	v_pk_mul_f32 v[116:117], v[116:117], v[152:153]
	v_lshlrev_b32_e32 v152, 16, v139
	v_and_b32_e32 v153, 0xffff0000, v139
	v_pk_mul_f32 v[118:119], v[118:119], v[152:153]
	v_cvt_pk_bf16_f32 v120, v120, v121
	v_cvt_pk_bf16_f32 v121, v122, v123
	v_cvt_pk_bf16_f32 v122, v116, v117
	v_cvt_pk_bf16_f32 v123, v118, v119
	global_store_dwordx4 v2, v[120:123], s[44:45] offset:256
	s_waitcnt vmcnt(15)
	v_lshlrev_b32_e32 v152, 16, v156
	v_and_b32_e32 v153, 0xffff0000, v156
	v_pk_mul_f32 v[112:113], v[112:113], v[152:153]
	v_lshlrev_b32_e32 v152, 16, v157
	v_and_b32_e32 v153, 0xffff0000, v157
	v_pk_mul_f32 v[114:115], v[114:115], v[152:153]
	v_lshlrev_b32_e32 v152, 16, v158
	v_and_b32_e32 v153, 0xffff0000, v158
	v_pk_mul_f32 v[108:109], v[108:109], v[152:153]
	v_lshlrev_b32_e32 v152, 16, v159
	v_and_b32_e32 v153, 0xffff0000, v159
	v_pk_mul_f32 v[110:111], v[110:111], v[152:153]
	v_cvt_pk_bf16_f32 v112, v112, v113
	v_cvt_pk_bf16_f32 v113, v114, v115
	v_cvt_pk_bf16_f32 v114, v108, v109
	v_cvt_pk_bf16_f32 v115, v110, v111
	v_add_u32_e32 v3, 0x10000, v2
	global_store_dwordx4 v3, v[112:115], s[44:45] offset:0
	s_waitcnt vmcnt(15)
	v_lshlrev_b32_e32 v152, 16, v186
	v_and_b32_e32 v153, 0xffff0000, v186
	v_pk_mul_f32 v[104:105], v[104:105], v[152:153]
	v_lshlrev_b32_e32 v152, 16, v187
	v_and_b32_e32 v153, 0xffff0000, v187
	v_pk_mul_f32 v[106:107], v[106:107], v[152:153]
	v_lshlrev_b32_e32 v152, 16, v188
	v_and_b32_e32 v153, 0xffff0000, v188
	v_pk_mul_f32 v[100:101], v[100:101], v[152:153]
	v_lshlrev_b32_e32 v152, 16, v189
	v_and_b32_e32 v153, 0xffff0000, v189
	v_pk_mul_f32 v[102:103], v[102:103], v[152:153]
	v_cvt_pk_bf16_f32 v104, v104, v105
	v_cvt_pk_bf16_f32 v105, v106, v107
	v_cvt_pk_bf16_f32 v106, v100, v101
	v_cvt_pk_bf16_f32 v107, v102, v103
	global_store_dwordx4 v3, v[104:107], s[44:45] offset:256
	s_waitcnt vmcnt(15)
	v_lshlrev_b32_e32 v152, 16, v190
	v_and_b32_e32 v153, 0xffff0000, v190
	v_pk_mul_f32 v[96:97], v[96:97], v[152:153]
	v_lshlrev_b32_e32 v152, 16, v191
	v_and_b32_e32 v153, 0xffff0000, v191
	v_pk_mul_f32 v[98:99], v[98:99], v[152:153]
	v_lshlrev_b32_e32 v152, 16, v192
	v_and_b32_e32 v153, 0xffff0000, v192
	v_pk_mul_f32 v[92:93], v[92:93], v[152:153]
	v_lshlrev_b32_e32 v152, 16, v193
	v_and_b32_e32 v153, 0xffff0000, v193
	v_pk_mul_f32 v[94:95], v[94:95], v[152:153]
	v_cvt_pk_bf16_f32 v96, v96, v97
	v_cvt_pk_bf16_f32 v97, v98, v99
	v_cvt_pk_bf16_f32 v98, v92, v93
	v_cvt_pk_bf16_f32 v99, v94, v95
	v_add_u32_e32 v154, 0x20000, v2
	global_store_dwordx4 v154, v[96:99], s[44:45] offset:0
	s_waitcnt vmcnt(15)
	v_lshlrev_b32_e32 v152, 16, v194
	v_and_b32_e32 v153, 0xffff0000, v194
	v_pk_mul_f32 v[88:89], v[88:89], v[152:153]
	v_lshlrev_b32_e32 v152, 16, v195
	v_and_b32_e32 v153, 0xffff0000, v195
	v_pk_mul_f32 v[90:91], v[90:91], v[152:153]
	v_lshlrev_b32_e32 v152, 16, v196
	v_and_b32_e32 v153, 0xffff0000, v196
	v_pk_mul_f32 v[84:85], v[84:85], v[152:153]
	v_lshlrev_b32_e32 v152, 16, v197
	v_and_b32_e32 v153, 0xffff0000, v197
	v_pk_mul_f32 v[86:87], v[86:87], v[152:153]
	v_cvt_pk_bf16_f32 v88, v88, v89
	v_cvt_pk_bf16_f32 v89, v90, v91
	v_cvt_pk_bf16_f32 v90, v84, v85
	v_cvt_pk_bf16_f32 v91, v86, v87
	global_store_dwordx4 v154, v[88:91], s[44:45] offset:256
	s_waitcnt vmcnt(15)
; __device__ __forceinline__ unsigned cvt_pk_bf16(float lo, float hi) { unsigned r; asm volatile("v_cvt_pk_bf16_f32 %0, %1, %2" : "=v"(r) : "v"(lo), "v"(hi)); return r; }
; #define PG8_BAR __builtin_amdgcn_s_barrier()
;     __device__ __forceinline__ void operator()(f32x4 (&acc)[2][2][4][2], const Unit& u, int wr, int wc, int fr, int fq) const {
;     ...
;                 for (int bj = 0; bj < 2; ++bj) {
;                     const u32x4 gc = *(const u32x4*)(Gt + r * NP + 4096 + col0 + bj * HALF);
;                     float fc[8]; unpack8(gc, fc);
;                     f32x4 v0 = acc[ai][bj][m][0], v1 = acc[ai][bj][m][1];
;                     u32x4 w; w.x = cvt_pk_bf16(v0[0] * fc[0], v0[1] * fc[1]); w.y = cvt_pk_bf16(v0[2] * fc[2], v0[3] * fc[3]);
;                     w.z = cvt_pk_bf16(v1[0] * fc[4], v1[1] * fc[5]); w.w = cvt_pk_bf16(v1[2] * fc[6], v1[3] * fc[7]);
;                     *(u32x4*)(O + r * DM + col0 + bj * HALF) = w;
;                     asm volatile("" ::: "memory");
;                 }
;             }
;     }
; template <class Epi>
; __device__ __forceinline__ void gemm_phase(LAS unsigned char* lds, const Gemm g, const StaticOrder& S, const Epi& E) {
;     ...
;         if (!has_next) break;
; #pragma unroll
;         for (int a = 0; a < 2; ++a)
; #pragma unroll
;             for (int b = 0; b < 2; ++b)
; #pragma unroll
;                 for (int m = 0; m < 4; ++m)
; #pragma unroll
;                     for (int n = 0; n < 2; ++n) acc[a][b][m][n] = (f32x4){0.f, 0.f, 0.f, 0.f};
;         cur = nxt; cA = nA; cB = nB; ++ui;
;         if (wr == 1) PG8_BAR;
	v_lshlrev_b32_e32 v152, 16, v198
	v_and_b32_e32 v153, 0xffff0000, v198
	v_pk_mul_f32 v[80:81], v[80:81], v[152:153]
	v_lshlrev_b32_e32 v152, 16, v199
	v_and_b32_e32 v153, 0xffff0000, v199
	v_pk_mul_f32 v[82:83], v[82:83], v[152:153]
	v_lshlrev_b32_e32 v152, 16, v200
	v_and_b32_e32 v153, 0xffff0000, v200
	v_pk_mul_f32 v[76:77], v[76:77], v[152:153]
	v_lshlrev_b32_e32 v152, 16, v201
	v_and_b32_e32 v153, 0xffff0000, v201
	v_pk_mul_f32 v[78:79], v[78:79], v[152:153]
	v_cvt_pk_bf16_f32 v80, v80, v81
	v_cvt_pk_bf16_f32 v81, v82, v83
	v_cvt_pk_bf16_f32 v82, v76, v77
	v_cvt_pk_bf16_f32 v83, v78, v79
	v_add_u32_e32 v3, 0x30000, v2
	global_store_dwordx4 v3, v[80:83], s[44:45] offset:0
	s_waitcnt vmcnt(15)
	v_lshlrev_b32_e32 v152, 16, v202
	v_and_b32_e32 v153, 0xffff0000, v202
	v_pk_mul_f32 v[72:73], v[72:73], v[152:153]
	v_lshlrev_b32_e32 v152, 16, v203
	v_and_b32_e32 v153, 0xffff0000, v203
	v_pk_mul_f32 v[74:75], v[74:75], v[152:153]
	v_lshlrev_b32_e32 v152, 16, v204
	v_and_b32_e32 v153, 0xffff0000, v204
	v_pk_mul_f32 v[68:69], v[68:69], v[152:153]
	v_lshlrev_b32_e32 v152, 16, v205
	v_and_b32_e32 v153, 0xffff0000, v205
	v_pk_mul_f32 v[70:71], v[70:71], v[152:153]
	v_cvt_pk_bf16_f32 v72, v72, v73
	v_cvt_pk_bf16_f32 v73, v74, v75
	v_cvt_pk_bf16_f32 v74, v68, v69
	v_cvt_pk_bf16_f32 v75, v70, v71
	global_store_dwordx4 v3, v[72:75], s[44:45] offset:256
	s_waitcnt vmcnt(15)
	v_lshlrev_b32_e32 v152, 16, v206
	v_and_b32_e32 v153, 0xffff0000, v206
	v_pk_mul_f32 v[64:65], v[64:65], v[152:153]
	v_lshlrev_b32_e32 v152, 16, v207
	v_and_b32_e32 v153, 0xffff0000, v207
	v_pk_mul_f32 v[66:67], v[66:67], v[152:153]
	v_lshlrev_b32_e32 v152, 16, v208
	v_and_b32_e32 v153, 0xffff0000, v208
	v_pk_mul_f32 v[60:61], v[60:61], v[152:153]
	v_lshlrev_b32_e32 v152, 16, v209
	v_and_b32_e32 v153, 0xffff0000, v209
	v_pk_mul_f32 v[62:63], v[62:63], v[152:153]
	v_cvt_pk_bf16_f32 v64, v64, v65
	v_cvt_pk_bf16_f32 v65, v66, v67
	v_cvt_pk_bf16_f32 v66, v60, v61
	v_cvt_pk_bf16_f32 v67, v62, v63
	v_add_u32_e32 v154, 0x80000, v2
	global_store_dwordx4 v154, v[64:67], s[44:45] offset:0
	s_waitcnt vmcnt(15)
	v_lshlrev_b32_e32 v152, 16, v222
	v_and_b32_e32 v153, 0xffff0000, v222
	v_pk_mul_f32 v[56:57], v[56:57], v[152:153]
	v_lshlrev_b32_e32 v152, 16, v223
	v_and_b32_e32 v153, 0xffff0000, v223
	v_pk_mul_f32 v[58:59], v[58:59], v[152:153]
	v_lshlrev_b32_e32 v152, 16, v224
	v_and_b32_e32 v153, 0xffff0000, v224
	v_pk_mul_f32 v[52:53], v[52:53], v[152:153]
	v_lshlrev_b32_e32 v152, 16, v225
	v_and_b32_e32 v153, 0xffff0000, v225
	v_pk_mul_f32 v[54:55], v[54:55], v[152:153]
	v_cvt_pk_bf16_f32 v56, v56, v57
	v_cvt_pk_bf16_f32 v57, v58, v59
	v_cvt_pk_bf16_f32 v58, v52, v53
	v_cvt_pk_bf16_f32 v59, v54, v55
	global_store_dwordx4 v154, v[56:59], s[44:45] offset:256
	s_waitcnt vmcnt(15)
	v_lshlrev_b32_e32 v152, 16, v226
	v_and_b32_e32 v153, 0xffff0000, v226
	v_pk_mul_f32 v[48:49], v[48:49], v[152:153]
	v_lshlrev_b32_e32 v152, 16, v227
	v_and_b32_e32 v153, 0xffff0000, v227
	v_pk_mul_f32 v[50:51], v[50:51], v[152:153]
	v_lshlrev_b32_e32 v152, 16, v228
	v_and_b32_e32 v153, 0xffff0000, v228
	v_pk_mul_f32 v[44:45], v[44:45], v[152:153]
	v_lshlrev_b32_e32 v152, 16, v229
	v_and_b32_e32 v153, 0xffff0000, v229
	v_pk_mul_f32 v[46:47], v[46:47], v[152:153]
	v_cvt_pk_bf16_f32 v48, v48, v49
	v_cvt_pk_bf16_f32 v49, v50, v51
	v_cvt_pk_bf16_f32 v50, v44, v45
	v_cvt_pk_bf16_f32 v51, v46, v47
	v_add_u32_e32 v3, 0x90000, v2
	global_store_dwordx4 v3, v[48:51], s[44:45] offset:0
	s_waitcnt vmcnt(15)
	v_lshlrev_b32_e32 v152, 16, v230
	v_and_b32_e32 v153, 0xffff0000, v230
	v_pk_mul_f32 v[40:41], v[40:41], v[152:153]
	v_lshlrev_b32_e32 v152, 16, v231
	v_and_b32_e32 v153, 0xffff0000, v231
	v_pk_mul_f32 v[42:43], v[42:43], v[152:153]
	v_lshlrev_b32_e32 v152, 16, v232
	v_and_b32_e32 v153, 0xffff0000, v232
	v_pk_mul_f32 v[36:37], v[36:37], v[152:153]
	v_lshlrev_b32_e32 v152, 16, v233
	v_and_b32_e32 v153, 0xffff0000, v233
	v_pk_mul_f32 v[38:39], v[38:39], v[152:153]
	v_cvt_pk_bf16_f32 v40, v40, v41
	v_cvt_pk_bf16_f32 v41, v42, v43
	v_cvt_pk_bf16_f32 v42, v36, v37
	v_cvt_pk_bf16_f32 v43, v38, v39
	global_store_dwordx4 v3, v[40:43], s[44:45] offset:256
	s_waitcnt vmcnt(15)
	v_lshlrev_b32_e32 v152, 16, v234
	v_and_b32_e32 v153, 0xffff0000, v234
	v_pk_mul_f32 v[32:33], v[32:33], v[152:153]
	v_lshlrev_b32_e32 v152, 16, v235
	v_and_b32_e32 v153, 0xffff0000, v235
	v_pk_mul_f32 v[34:35], v[34:35], v[152:153]
	v_lshlrev_b32_e32 v152, 16, v236
	v_and_b32_e32 v153, 0xffff0000, v236
	v_pk_mul_f32 v[28:29], v[28:29], v[152:153]
	v_lshlrev_b32_e32 v152, 16, v237
	v_and_b32_e32 v153, 0xffff0000, v237
	v_pk_mul_f32 v[30:31], v[30:31], v[152:153]
	v_cvt_pk_bf16_f32 v32, v32, v33
	v_cvt_pk_bf16_f32 v33, v34, v35
	v_cvt_pk_bf16_f32 v34, v28, v29
	v_cvt_pk_bf16_f32 v35, v30, v31
	v_add_u32_e32 v154, 0xa0000, v2
	global_store_dwordx4 v154, v[32:35], s[44:45] offset:0
	s_waitcnt vmcnt(15)
	v_lshlrev_b32_e32 v152, 16, v238
	v_and_b32_e32 v153, 0xffff0000, v238
	v_pk_mul_f32 v[24:25], v[24:25], v[152:153]
	v_lshlrev_b32_e32 v152, 16, v239
	v_and_b32_e32 v153, 0xffff0000, v239
	v_pk_mul_f32 v[26:27], v[26:27], v[152:153]
	v_lshlrev_b32_e32 v152, 16, v240
	v_and_b32_e32 v153, 0xffff0000, v240
	v_pk_mul_f32 v[20:21], v[20:21], v[152:153]
	v_lshlrev_b32_e32 v152, 16, v241
	v_and_b32_e32 v153, 0xffff0000, v241
	v_pk_mul_f32 v[22:23], v[22:23], v[152:153]
	v_cvt_pk_bf16_f32 v24, v24, v25
	v_cvt_pk_bf16_f32 v25, v26, v27
	v_cvt_pk_bf16_f32 v26, v20, v21
	v_cvt_pk_bf16_f32 v27, v22, v23
	global_store_dwordx4 v154, v[24:27], s[44:45] offset:256
	s_waitcnt vmcnt(15)
	v_lshlrev_b32_e32 v152, 16, v242
	v_and_b32_e32 v153, 0xffff0000, v242
	v_pk_mul_f32 v[16:17], v[16:17], v[152:153]
	v_lshlrev_b32_e32 v152, 16, v243
	v_and_b32_e32 v153, 0xffff0000, v243
	v_pk_mul_f32 v[18:19], v[18:19], v[152:153]
	v_lshlrev_b32_e32 v152, 16, v244
	v_and_b32_e32 v153, 0xffff0000, v244
	v_pk_mul_f32 v[12:13], v[12:13], v[152:153]
	v_lshlrev_b32_e32 v152, 16, v245
	v_and_b32_e32 v153, 0xffff0000, v245
	v_pk_mul_f32 v[14:15], v[14:15], v[152:153]
	v_cvt_pk_bf16_f32 v16, v16, v17
	v_cvt_pk_bf16_f32 v17, v18, v19
	v_cvt_pk_bf16_f32 v18, v12, v13
	v_cvt_pk_bf16_f32 v19, v14, v15
	v_add_u32_e32 v3, 0xb0000, v2
	global_store_dwordx4 v3, v[16:19], s[44:45] offset:0
	s_waitcnt vmcnt(15)
	v_lshlrev_b32_e32 v152, 16, v246
	v_and_b32_e32 v153, 0xffff0000, v246
	v_pk_mul_f32 v[8:9], v[8:9], v[152:153]
	v_lshlrev_b32_e32 v152, 16, v247
	v_and_b32_e32 v153, 0xffff0000, v247
	v_pk_mul_f32 v[10:11], v[10:11], v[152:153]
	v_lshlrev_b32_e32 v152, 16, v248
	v_and_b32_e32 v153, 0xffff0000, v248
	v_pk_mul_f32 v[4:5], v[4:5], v[152:153]
	v_lshlrev_b32_e32 v152, 16, v249
	v_and_b32_e32 v153, 0xffff0000, v249
	v_pk_mul_f32 v[6:7], v[6:7], v[152:153]
	v_cvt_pk_bf16_f32 v8, v8, v9
	v_cvt_pk_bf16_f32 v9, v10, v11
	v_cvt_pk_bf16_f32 v10, v4, v5
	v_cvt_pk_bf16_f32 v11, v6, v7
	global_store_dwordx4 v3, v[8:11], s[44:45] offset:256
	s_andn2_b64 vcc, exec, s[40:41]
	s_cbranch_vccnz .LBB0_867
	s_andn2_b64 vcc, exec, s[42:43]
	s_cbranch_vccnz .LBB0_866
	s_barrier
	s_branch .LBB0_866

; template <bool HAS_T>
; __device__ __forceinline__ void norm_rows(const float* xin, const bf16_t* t, const float* gpost, float* xout, const float* gpre, bf16_t* U, int gw, int ngw, int lane) {
;     ...
;     if (gw < TT) {
;         const size_t rb = (size_t)gw * DM;
; #pragma unroll
;         for (int j = 0; j < 4; ++j) { const int c = j * 512 + lane * 8; xn[j][0] = *(const f32x4*)(xin + rb + c); xn[j][1] = *(const f32x4*)(xin + rb + c + 4);
;             if constexpr (HAS_T) tn[j] = *(const u32x4*)(t + rb + c); }
;     }
;     for (int m = gw; m < TT; m += ngw) {
;         const size_t rb = (size_t)m * DM;
; #pragma unroll
;         for (int j = 0; j < 4; ++j) { xa[j][0] = xn[j][0]; xa[j][1] = xn[j][1]; if constexpr (HAS_T) tv[j] = tn[j]; }
;         if (m + ngw < TT) {
;             const size_t rn = (size_t)(m + ngw) * DM;
; #pragma unroll
;             for (int j = 0; j < 4; ++j) { const int c = j * 512 + lane * 8; xn[j][0] = *(const f32x4*)(xin + rn + c); xn[j][1] = *(const f32x4*)(xin + rn + c + 4);
;                 if constexpr (HAS_T) tn[j] = *(const u32x4*)(t + rn + c); }
;         }
.LBB0_1223:
	s_ashr_i32 s4, s2, 6
	v_readlane_b32 s2, v253, 2
	s_add_i32 s24, s4, s2
	v_and_b32_e32 v114, 63, v1
	s_mov_b64 s[44:45], s[0:1]
	s_cmpk_gt_i32 s24, 0x3fff
	s_cbranch_scc1 .LBB0_1230
	s_lshl_b64 s[26:27], s[26:27], 2
	s_waitcnt lgkmcnt(0)
	s_add_u32 s26, s40, s26
	s_addc_u32 s27, s41, s27
	s_ashr_i32 s25, s24, 31
	s_lshl_b64 s[40:41], s[24:25], 13
	s_add_u32 s46, s34, s40
	s_addc_u32 s47, s35, s41
	s_lshl_b64 s[42:43], s[24:25], 12
	s_add_u32 s48, s28, s42
	s_addc_u32 s49, s29, s43
	v_lshlrev_b32_e32 v100, 4, v114
	v_mov_b32_e32 v101, v0
	v_lshl_add_u64 v[2:3], s[48:49], 0, v[100:101]
	s_mov_b64 s[12:13], 0x1c700000
	s_mov_b32 s2, 0x1c700000
	v_lshlrev_b32_e32 v98, 5, v114
	v_lshl_add_u64 v[4:5], v[2:3], 0, s[12:13]
	v_add_co_u32_e32 v2, vcc, s2, v2
	v_or_b32_e32 v6, 0x1000, v98
	v_or_b32_e32 v8, 0x1800, v98
	v_addc_co_u32_e32 v3, vcc, 0, v3, vcc
	global_load_dwordx4 v[74:77], v98, s[46:47] offset:16 nt
	global_load_dwordx4 v[78:81], v98, s[46:47]
	global_load_dwordx4 v[66:69], v98, s[46:47] offset:2064 nt
	global_load_dwordx4 v[70:73], v98, s[46:47] offset:2048 nt
	global_load_dwordx4 v[58:61], v6, s[46:47] offset:16 nt
	global_load_dwordx4 v[62:65], v6, s[46:47]
	global_load_dwordx4 v[90:93], v[4:5], off offset:1024
	global_load_dwordx4 v[86:89], v[4:5], off offset:2048
	global_load_dwordx4 v[50:53], v8, s[46:47] offset:16 nt
	global_load_dwordx4 v[54:57], v8, s[46:47]
	global_load_dwordx4 v[82:85], v[4:5], off offset:3072
	global_load_dwordx4 v[94:97], v[2:3], off
	v_mov_b32_e32 v99, v0
	v_mov_b32_e32 v7, v0
	v_mov_b32_e32 v9, v0
	s_cmp_lg_u64 s[36:37], 0
	v_readlane_b32 s5, v255, 1
	v_lshl_add_u64 v[102:103], s[36:37], 0, v[98:99]
	v_lshl_add_u64 v[104:105], s[36:37], 0, v[6:7]
	v_lshl_add_u64 v[106:107], s[36:37], 0, v[8:9]
	v_lshl_add_u64 v[108:109], s[26:27], 0, v[98:99]
	v_lshl_add_u64 v[110:111], s[26:27], 0, v[6:7]
	v_lshl_add_u64 v[112:113], s[26:27], 0, v[8:9]
	s_cselect_b64 s[26:27], -1, 0
	s_add_i32 s36, s5, s4
	s_ashr_i32 s37, s36, 31
	s_lshl_b64 s[46:47], s[36:37], 12
	s_add_u32 s28, s28, s46
	s_load_dwordx2 s[44:45], s[44:45], 0xc8
	s_addc_u32 s29, s29, s47
	s_add_u32 s30, s30, s40
	s_addc_u32 s31, s31, s41
	s_lshl_b64 s[36:37], s[36:37], 13
	s_add_u32 s34, s34, s36
	s_addc_u32 s35, s35, s37
	s_waitcnt lgkmcnt(0)
	s_add_u32 s36, s44, s42
	s_mov_b32 s2, s24
	s_addc_u32 s37, s45, s43
	s_waitcnt vmcnt(11)
	v_mov_b64_e32 v[2:3], v[74:75]
	s_waitcnt vmcnt(9)
	v_mov_b64_e32 v[10:11], v[66:67]
	s_waitcnt vmcnt(8)
	v_mov_b64_e32 v[14:15], v[70:71]
	v_mov_b64_e32 v[6:7], v[78:79]
	s_waitcnt vmcnt(6)
	v_mov_b64_e32 v[26:27], v[62:63]
	v_mov_b64_e32 v[30:31], v[58:59]
	s_waitcnt vmcnt(2)
	v_mov_b64_e32 v[34:35], v[54:55]
	v_mov_b64_e32 v[38:39], v[50:51]
	s_waitcnt vmcnt(1)
	v_mov_b64_e32 v[46:47], v[82:83]
	v_mov_b64_e32 v[42:43], v[86:87]
	v_mov_b64_e32 v[22:23], v[90:91]
	s_waitcnt vmcnt(0)
	v_mov_b64_e32 v[18:19], v[94:95]
	v_mov_b64_e32 v[12:13], v[68:69]
	v_mov_b64_e32 v[16:17], v[72:73]
	v_mov_b64_e32 v[4:5], v[76:77]
	v_mov_b64_e32 v[8:9], v[80:81]
	v_mov_b64_e32 v[28:29], v[64:65]
	v_mov_b64_e32 v[32:33], v[60:61]
	v_mov_b64_e32 v[36:37], v[56:57]
	v_mov_b64_e32 v[40:41], v[52:53]
	v_mov_b64_e32 v[48:49], v[84:85]
	v_mov_b64_e32 v[44:45], v[88:89]
	v_mov_b64_e32 v[24:25], v[92:93]
	v_mov_b64_e32 v[20:21], v[96:97]
	s_branch .LBB0_1226
